# mid-segment s_setprio 0 / s_setprio 1 pairs between the two 16-MFMA blocks of a K-loop segment deleted (priority stays raised across the 32 MFMAs)
# speedup vs baseline: 1.0048x; 1.0048x over previous
.LBB0_333:
	s_add_i32 s51, s50, 2
	s_add_u32 s52, s42, 0x80
	s_addc_u32 s53, s43, 0
	s_add_i32 s54, 0, 0x10000
	s_cmp_eq_u32 s87, s50
	s_cselect_b32 s79, s1, s53
	s_cselect_b32 s78, s0, s52
	v_add_u32_e32 v144, s54, v147
	s_cselect_b32 s53, s75, s49
	s_cselect_b32 s52, s74, s48
	s_add_i32 s50, 0, 0x14000
	s_waitcnt lgkmcnt(0)
	ds_read_b128 v[140:143], v144
	ds_read_b128 v[162:165], v144 offset:1024
	ds_read_b128 v[166:169], v144 offset:2048
	ds_read_b128 v[170:173], v144 offset:3072
	v_add_u32_e32 v144, s50, v147
	ds_read_b128 v[174:177], v144
	ds_read_b128 v[178:181], v144 offset:1024
	ds_read_b128 v[182:185], v144 offset:2048
	ds_read_b128 v[186:189], v144 offset:3072
	v_lshl_add_u64 v[144:145], s[42:43], 0, v[136:137]
	s_add_i32 m0, s9, 0xc000
	ds_read_b128 v[190:193], v149
	ds_read_b128 v[194:197], v149 offset:1024
	ds_read_b128 v[198:201], v149 offset:2048
	ds_read_b128 v[202:205], v149 offset:3072
	ds_read_b128 v[206:209], v149 offset:4096
	ds_read_b128 v[210:213], v149 offset:5120
	ds_read_b128 v[214:217], v149 offset:6144
	ds_read_b128 v[218:221], v149 offset:7168
	global_load_lds_dwordx4 v[144:145], off
	v_lshl_add_u64 v[144:145], s[42:43], 0, v[138:139]
	s_add_i32 m0, s9, 0xe000
	s_nop 0
	global_load_lds_dwordx4 v[144:145], off
	s_waitcnt vmcnt(8)
	s_waitcnt lgkmcnt(0)
	s_barrier
	s_setprio 1
	s_waitcnt lgkmcnt(0)
	v_mfma_f32_16x16x32_bf16 v[126:129], v[140:143], v[190:193], v[126:129]
	v_mfma_f32_16x16x32_bf16 v[122:125], v[166:169], v[190:193], v[122:125]
	v_mfma_f32_16x16x32_bf16 v[110:113], v[140:143], v[198:201], v[110:113]
	v_mfma_f32_16x16x32_bf16 v[106:109], v[166:169], v[198:201], v[106:109]
	v_mfma_f32_16x16x32_bf16 v[92:95], v[140:143], v[206:209], v[92:95]
	v_mfma_f32_16x16x32_bf16 v[88:91], v[166:169], v[206:209], v[88:91]
	v_mfma_f32_16x16x32_bf16 v[76:79], v[140:143], v[214:217], v[76:79]
	v_mfma_f32_16x16x32_bf16 v[72:75], v[166:169], v[214:217], v[72:75]
	v_mfma_f32_16x16x32_bf16 v[126:129], v[162:165], v[194:197], v[126:129]
	v_mfma_f32_16x16x32_bf16 v[122:125], v[170:173], v[194:197], v[122:125]
	v_mfma_f32_16x16x32_bf16 v[110:113], v[162:165], v[202:205], v[110:113]
	v_mfma_f32_16x16x32_bf16 v[106:109], v[170:173], v[202:205], v[106:109]
	v_mfma_f32_16x16x32_bf16 v[92:95], v[162:165], v[210:213], v[92:95]
	v_mfma_f32_16x16x32_bf16 v[88:91], v[170:173], v[210:213], v[88:91]
	v_mfma_f32_16x16x32_bf16 v[76:79], v[162:165], v[218:221], v[76:79]
	v_mfma_f32_16x16x32_bf16 v[72:75], v[170:173], v[218:221], v[72:75]
	v_mfma_f32_16x16x32_bf16 v[118:121], v[174:177], v[190:193], v[118:121]
	v_mfma_f32_16x16x32_bf16 v[114:117], v[182:185], v[190:193], v[114:117]
	v_mfma_f32_16x16x32_bf16 v[102:105], v[174:177], v[198:201], v[102:105]
	v_mfma_f32_16x16x32_bf16 v[98:101], v[182:185], v[198:201], v[98:101]
	v_mfma_f32_16x16x32_bf16 v[84:87], v[174:177], v[206:209], v[84:87]
	v_mfma_f32_16x16x32_bf16 v[80:83], v[182:185], v[206:209], v[80:83]
	v_mfma_f32_16x16x32_bf16 v[68:71], v[174:177], v[214:217], v[68:71]
	v_mfma_f32_16x16x32_bf16 v[64:67], v[182:185], v[214:217], v[64:67]
	v_mfma_f32_16x16x32_bf16 v[118:121], v[178:181], v[194:197], v[118:121]
	v_mfma_f32_16x16x32_bf16 v[114:117], v[186:189], v[194:197], v[114:117]
	v_mfma_f32_16x16x32_bf16 v[102:105], v[178:181], v[202:205], v[102:105]
	v_mfma_f32_16x16x32_bf16 v[98:101], v[186:189], v[202:205], v[98:101]
	v_mfma_f32_16x16x32_bf16 v[84:87], v[178:181], v[210:213], v[84:87]
	v_mfma_f32_16x16x32_bf16 v[80:83], v[186:189], v[210:213], v[80:83]
	v_mfma_f32_16x16x32_bf16 v[68:71], v[178:181], v[218:221], v[68:71]
	v_mfma_f32_16x16x32_bf16 v[64:67], v[186:189], v[218:221], v[64:67]
	s_setprio 0
	s_barrier
	s_add_i32 s54, s54, s8
	v_lshl_add_u64 v[144:145], s[52:53], 0, v[96:97]
	s_mov_b32 m0, s54
	ds_read_b128 v[190:193], v149 offset:16384
	ds_read_b128 v[194:197], v149 offset:17408
	ds_read_b128 v[198:201], v149 offset:18432
	ds_read_b128 v[202:205], v149 offset:19456
	ds_read_b128 v[206:209], v149 offset:20480
	ds_read_b128 v[210:213], v149 offset:21504
	ds_read_b128 v[214:217], v149 offset:22528
	ds_read_b128 v[218:221], v149 offset:23552
	global_load_lds_dwordx4 v[144:145], off
	s_add_i32 m0, s54, 0x2000
	v_lshl_add_u64 v[150:151], s[52:53], 0, v[134:135]
	s_add_u32 s52, s52, s34
	s_addc_u32 s53, s53, s35
	s_add_i32 s50, s50, s8
	global_load_lds_dwordx4 v[150:151], off
	v_lshl_add_u64 v[222:223], s[52:53], 0, v[96:97]
	s_mov_b32 m0, s50
	v_lshl_add_u64 v[224:225], s[52:53], 0, v[134:135]
	global_load_lds_dwordx4 v[222:223], off
	s_add_i32 m0, s50, 0x2000
	v_lshl_add_u64 v[226:227], s[78:79], 0, v[130:131]
	global_load_lds_dwordx4 v[224:225], off
	s_mov_b32 m0, s9
	v_lshl_add_u64 v[228:229], s[78:79], 0, v[132:133]
	global_load_lds_dwordx4 v[226:227], off
	s_mov_b32 m0, s98
	s_nop 0
	global_load_lds_dwordx4 v[228:229], off
	s_waitcnt vmcnt(8)
	s_waitcnt lgkmcnt(0)
	s_barrier
	s_setprio 1
	s_waitcnt lgkmcnt(0)
	v_mfma_f32_16x16x32_bf16 v[60:63], v[140:143], v[190:193], v[60:63]
	v_mfma_f32_16x16x32_bf16 v[56:59], v[166:169], v[190:193], v[56:59]
	v_mfma_f32_16x16x32_bf16 v[44:47], v[140:143], v[198:201], v[44:47]
	v_mfma_f32_16x16x32_bf16 v[40:43], v[166:169], v[198:201], v[40:43]
	v_mfma_f32_16x16x32_bf16 v[28:31], v[140:143], v[206:209], v[28:31]
	v_mfma_f32_16x16x32_bf16 v[24:27], v[166:169], v[206:209], v[24:27]
	v_mfma_f32_16x16x32_bf16 v[12:15], v[140:143], v[214:217], v[12:15]
	v_mfma_f32_16x16x32_bf16 v[8:11], v[166:169], v[214:217], v[8:11]
	v_mfma_f32_16x16x32_bf16 v[60:63], v[162:165], v[194:197], v[60:63]
	v_mfma_f32_16x16x32_bf16 v[56:59], v[170:173], v[194:197], v[56:59]
	v_mfma_f32_16x16x32_bf16 v[44:47], v[162:165], v[202:205], v[44:47]
	v_mfma_f32_16x16x32_bf16 v[40:43], v[170:173], v[202:205], v[40:43]
	v_mfma_f32_16x16x32_bf16 v[28:31], v[162:165], v[210:213], v[28:31]
	v_mfma_f32_16x16x32_bf16 v[24:27], v[170:173], v[210:213], v[24:27]
	v_mfma_f32_16x16x32_bf16 v[12:15], v[162:165], v[218:221], v[12:15]
	v_mfma_f32_16x16x32_bf16 v[8:11], v[170:173], v[218:221], v[8:11]
	v_mfma_f32_16x16x32_bf16 v[52:55], v[174:177], v[190:193], v[52:55]
	v_mfma_f32_16x16x32_bf16 v[48:51], v[182:185], v[190:193], v[48:51]
	v_mfma_f32_16x16x32_bf16 v[36:39], v[174:177], v[198:201], v[36:39]
	v_mfma_f32_16x16x32_bf16 v[32:35], v[182:185], v[198:201], v[32:35]
	v_mfma_f32_16x16x32_bf16 v[20:23], v[174:177], v[206:209], v[20:23]
	v_mfma_f32_16x16x32_bf16 v[16:19], v[182:185], v[206:209], v[16:19]
	v_mfma_f32_16x16x32_bf16 v[4:7], v[174:177], v[214:217], v[4:7]
	v_mfma_f32_16x16x32_bf16 v[0:3], v[182:185], v[214:217], v[0:3]
	v_mfma_f32_16x16x32_bf16 v[52:55], v[178:181], v[194:197], v[52:55]
	v_mfma_f32_16x16x32_bf16 v[48:51], v[186:189], v[194:197], v[48:51]
	v_mfma_f32_16x16x32_bf16 v[36:39], v[178:181], v[202:205], v[36:39]
	v_mfma_f32_16x16x32_bf16 v[32:35], v[186:189], v[202:205], v[32:35]
	v_mfma_f32_16x16x32_bf16 v[20:23], v[178:181], v[210:213], v[20:23]
	v_mfma_f32_16x16x32_bf16 v[16:19], v[186:189], v[210:213], v[16:19]
	v_mfma_f32_16x16x32_bf16 v[4:7], v[178:181], v[218:221], v[4:7]
	v_mfma_f32_16x16x32_bf16 v[0:3], v[186:189], v[218:221], v[0:3]
	s_setprio 0
	s_barrier
	s_add_i32 s50, 0, 0x18000
	v_add_u32_e32 v161, s50, v147
	s_add_i32 s54, 0, 0x1c000
	ds_read_b128 v[140:143], v161
	ds_read_b128 v[162:165], v161 offset:1024
	ds_read_b128 v[166:169], v161 offset:2048
	ds_read_b128 v[170:173], v161 offset:3072
	v_add_u32_e32 v161, s54, v147
	ds_read_b128 v[174:177], v161
	ds_read_b128 v[178:181], v161 offset:1024
	ds_read_b128 v[182:185], v161 offset:2048
	ds_read_b128 v[186:189], v161 offset:3072
	s_add_u32 s52, s78, s34
	s_addc_u32 s53, s79, s35
	s_mov_b32 m0, s99
	v_lshl_add_u64 v[230:231], s[52:53], 0, v[130:131]
	ds_read_b128 v[190:193], v149 offset:32768
	ds_read_b128 v[194:197], v149 offset:33792
	ds_read_b128 v[198:201], v149 offset:34816
	ds_read_b128 v[202:205], v149 offset:35840
	ds_read_b128 v[206:209], v149 offset:36864
	ds_read_b128 v[210:213], v149 offset:37888
	ds_read_b128 v[214:217], v149 offset:38912
	ds_read_b128 v[218:221], v149 offset:39936
	global_load_lds_dwordx4 v[230:231], off
	v_lshl_add_u64 v[230:231], s[52:53], 0, v[132:133]
	s_mov_b32 m0, s76
	s_nop 0
	global_load_lds_dwordx4 v[230:231], off
	s_waitcnt vmcnt(8)
	s_waitcnt lgkmcnt(0)
	s_barrier
	s_setprio 1
	s_waitcnt lgkmcnt(0)
	v_mfma_f32_16x16x32_bf16 v[126:129], v[140:143], v[190:193], v[126:129]
	v_mfma_f32_16x16x32_bf16 v[122:125], v[166:169], v[190:193], v[122:125]
	v_mfma_f32_16x16x32_bf16 v[110:113], v[140:143], v[198:201], v[110:113]
	v_mfma_f32_16x16x32_bf16 v[106:109], v[166:169], v[198:201], v[106:109]
	v_mfma_f32_16x16x32_bf16 v[92:95], v[140:143], v[206:209], v[92:95]
	v_mfma_f32_16x16x32_bf16 v[88:91], v[166:169], v[206:209], v[88:91]
	v_mfma_f32_16x16x32_bf16 v[76:79], v[140:143], v[214:217], v[76:79]
	v_mfma_f32_16x16x32_bf16 v[72:75], v[166:169], v[214:217], v[72:75]
	v_mfma_f32_16x16x32_bf16 v[126:129], v[162:165], v[194:197], v[126:129]
	v_mfma_f32_16x16x32_bf16 v[122:125], v[170:173], v[194:197], v[122:125]
	v_mfma_f32_16x16x32_bf16 v[110:113], v[162:165], v[202:205], v[110:113]
	v_mfma_f32_16x16x32_bf16 v[106:109], v[170:173], v[202:205], v[106:109]
	v_mfma_f32_16x16x32_bf16 v[92:95], v[162:165], v[210:213], v[92:95]
	v_mfma_f32_16x16x32_bf16 v[88:91], v[170:173], v[210:213], v[88:91]
	v_mfma_f32_16x16x32_bf16 v[76:79], v[162:165], v[218:221], v[76:79]
	v_mfma_f32_16x16x32_bf16 v[72:75], v[170:173], v[218:221], v[72:75]
	v_mfma_f32_16x16x32_bf16 v[118:121], v[174:177], v[190:193], v[118:121]
	v_mfma_f32_16x16x32_bf16 v[114:117], v[182:185], v[190:193], v[114:117]
	v_mfma_f32_16x16x32_bf16 v[102:105], v[174:177], v[198:201], v[102:105]
	v_mfma_f32_16x16x32_bf16 v[98:101], v[182:185], v[198:201], v[98:101]
	v_mfma_f32_16x16x32_bf16 v[84:87], v[174:177], v[206:209], v[84:87]
	v_mfma_f32_16x16x32_bf16 v[80:83], v[182:185], v[206:209], v[80:83]
	v_mfma_f32_16x16x32_bf16 v[68:71], v[174:177], v[214:217], v[68:71]
	v_mfma_f32_16x16x32_bf16 v[64:67], v[182:185], v[214:217], v[64:67]
	v_mfma_f32_16x16x32_bf16 v[118:121], v[178:181], v[194:197], v[118:121]
	v_mfma_f32_16x16x32_bf16 v[114:117], v[186:189], v[194:197], v[114:117]
	v_mfma_f32_16x16x32_bf16 v[102:105], v[178:181], v[202:205], v[102:105]
	v_mfma_f32_16x16x32_bf16 v[98:101], v[186:189], v[202:205], v[98:101]
	v_mfma_f32_16x16x32_bf16 v[84:87], v[178:181], v[210:213], v[84:87]
	v_mfma_f32_16x16x32_bf16 v[80:83], v[186:189], v[210:213], v[80:83]
	v_mfma_f32_16x16x32_bf16 v[68:71], v[178:181], v[218:221], v[68:71]
	v_mfma_f32_16x16x32_bf16 v[64:67], v[186:189], v[218:221], v[64:67]
	s_setprio 0
	s_barrier
	s_add_i32 s50, s50, s8
	v_lshl_add_u64 v[144:145], v[144:145], 0, s[12:13]
	s_mov_b32 m0, s50
	ds_read_b128 v[190:193], v149 offset:49152
	ds_read_b128 v[194:197], v149 offset:50176
	ds_read_b128 v[198:201], v149 offset:51200
	ds_read_b128 v[202:205], v149 offset:52224
	ds_read_b128 v[206:209], v149 offset:53248
	ds_read_b128 v[210:213], v149 offset:54272
	ds_read_b128 v[214:217], v149 offset:55296
	ds_read_b128 v[218:221], v149 offset:56320
	global_load_lds_dwordx4 v[144:145], off
	v_lshl_add_u64 v[144:145], v[150:151], 0, s[12:13]
	s_add_i32 m0, s50, 0x2000
	s_add_i32 s50, s54, s8
	global_load_lds_dwordx4 v[144:145], off
	v_lshl_add_u64 v[144:145], v[222:223], 0, s[12:13]
	s_mov_b32 m0, s50
	s_nop 0
	global_load_lds_dwordx4 v[144:145], off
	v_lshl_add_u64 v[144:145], v[224:225], 0, s[12:13]
	s_add_i32 m0, s50, 0x2000
	s_nop 0
	global_load_lds_dwordx4 v[144:145], off
	v_lshl_add_u64 v[144:145], v[226:227], 0, s[12:13]
	s_mov_b32 m0, s77
	s_nop 0
	global_load_lds_dwordx4 v[144:145], off
	v_lshl_add_u64 v[144:145], v[228:229], 0, s[12:13]
	s_mov_b32 m0, s86
	s_nop 0
	global_load_lds_dwordx4 v[144:145], off
	s_waitcnt vmcnt(8)
	s_waitcnt lgkmcnt(0)
	s_barrier
	s_setprio 1
	s_waitcnt lgkmcnt(0)
	v_mfma_f32_16x16x32_bf16 v[60:63], v[140:143], v[190:193], v[60:63]
	v_mfma_f32_16x16x32_bf16 v[56:59], v[166:169], v[190:193], v[56:59]
	v_mfma_f32_16x16x32_bf16 v[44:47], v[140:143], v[198:201], v[44:47]
	v_mfma_f32_16x16x32_bf16 v[40:43], v[166:169], v[198:201], v[40:43]
	v_mfma_f32_16x16x32_bf16 v[28:31], v[140:143], v[206:209], v[28:31]
	v_mfma_f32_16x16x32_bf16 v[24:27], v[166:169], v[206:209], v[24:27]
	v_mfma_f32_16x16x32_bf16 v[12:15], v[140:143], v[214:217], v[12:15]
	v_mfma_f32_16x16x32_bf16 v[8:11], v[166:169], v[214:217], v[8:11]
	v_mfma_f32_16x16x32_bf16 v[60:63], v[162:165], v[194:197], v[60:63]
	v_mfma_f32_16x16x32_bf16 v[56:59], v[170:173], v[194:197], v[56:59]
	v_mfma_f32_16x16x32_bf16 v[44:47], v[162:165], v[202:205], v[44:47]
	v_mfma_f32_16x16x32_bf16 v[40:43], v[170:173], v[202:205], v[40:43]
	v_mfma_f32_16x16x32_bf16 v[28:31], v[162:165], v[210:213], v[28:31]
	v_mfma_f32_16x16x32_bf16 v[24:27], v[170:173], v[210:213], v[24:27]
	v_mfma_f32_16x16x32_bf16 v[12:15], v[162:165], v[218:221], v[12:15]
	v_mfma_f32_16x16x32_bf16 v[8:11], v[170:173], v[218:221], v[8:11]
	v_mfma_f32_16x16x32_bf16 v[52:55], v[174:177], v[190:193], v[52:55]
	v_mfma_f32_16x16x32_bf16 v[48:51], v[182:185], v[190:193], v[48:51]
	v_mfma_f32_16x16x32_bf16 v[36:39], v[174:177], v[198:201], v[36:39]
	v_mfma_f32_16x16x32_bf16 v[32:35], v[182:185], v[198:201], v[32:35]
	v_mfma_f32_16x16x32_bf16 v[20:23], v[174:177], v[206:209], v[20:23]
	v_mfma_f32_16x16x32_bf16 v[16:19], v[182:185], v[206:209], v[16:19]
	v_mfma_f32_16x16x32_bf16 v[4:7], v[174:177], v[214:217], v[4:7]
	v_mfma_f32_16x16x32_bf16 v[0:3], v[182:185], v[214:217], v[0:3]
	v_mfma_f32_16x16x32_bf16 v[52:55], v[178:181], v[194:197], v[52:55]
	v_mfma_f32_16x16x32_bf16 v[48:51], v[186:189], v[194:197], v[48:51]
	v_mfma_f32_16x16x32_bf16 v[36:39], v[178:181], v[202:205], v[36:39]
	v_mfma_f32_16x16x32_bf16 v[32:35], v[186:189], v[202:205], v[32:35]
	v_mfma_f32_16x16x32_bf16 v[20:23], v[178:181], v[210:213], v[20:23]
	v_mfma_f32_16x16x32_bf16 v[16:19], v[186:189], v[210:213], v[16:19]
	v_mfma_f32_16x16x32_bf16 v[4:7], v[178:181], v[218:221], v[4:7]
	v_mfma_f32_16x16x32_bf16 v[0:3], v[186:189], v[218:221], v[0:3]
	s_setprio 0
	s_barrier
	s_add_u32 s42, s42, 0x100
	s_addc_u32 s43, s43, 0
	s_add_u32 s48, s48, 0x100
	s_addc_u32 s49, s49, 0
	s_cmp_ge_u32 s51, s64
	s_mov_b32 s50, s51
	s_cbranch_scc0 .LBB0_333

.Lk_peel:
	s_add_i32 s51, s50, 2
	s_add_u32 s52, s42, 0x80
	s_addc_u32 s53, s43, 0
	s_add_i32 s54, 0, 0x10000
	s_cmp_eq_u32 s87, s50
	s_cselect_b32 s79, s1, s53
	s_cselect_b32 s78, s0, s52
	v_add_u32_e32 v144, s54, v147
	s_cselect_b32 s53, s75, s49
	s_cselect_b32 s52, s74, s48
	s_add_i32 s50, 0, 0x14000
	s_waitcnt lgkmcnt(0)
	ds_read_b128 v[140:143], v144
	ds_read_b128 v[162:165], v144 offset:1024
	ds_read_b128 v[166:169], v144 offset:2048
	ds_read_b128 v[170:173], v144 offset:3072
	v_add_u32_e32 v144, s50, v147
	ds_read_b128 v[174:177], v144
	ds_read_b128 v[178:181], v144 offset:1024
	ds_read_b128 v[182:185], v144 offset:2048
	ds_read_b128 v[186:189], v144 offset:3072
	ds_read_b128 v[190:193], v149
	ds_read_b128 v[194:197], v149 offset:1024
	ds_read_b128 v[198:201], v149 offset:2048
	ds_read_b128 v[202:205], v149 offset:3072
	ds_read_b128 v[206:209], v149 offset:4096
	ds_read_b128 v[210:213], v149 offset:5120
	ds_read_b128 v[214:217], v149 offset:6144
	ds_read_b128 v[218:221], v149 offset:7168
	s_waitcnt vmcnt(16)
	s_waitcnt lgkmcnt(0)
	s_barrier
	s_setprio 1
	s_waitcnt lgkmcnt(0)
	v_mfma_f32_16x16x32_bf16 v[126:129], v[140:143], v[190:193], 0
	v_mfma_f32_16x16x32_bf16 v[122:125], v[166:169], v[190:193], 0
	v_mfma_f32_16x16x32_bf16 v[110:113], v[140:143], v[198:201], 0
	v_mfma_f32_16x16x32_bf16 v[106:109], v[166:169], v[198:201], 0
	v_mfma_f32_16x16x32_bf16 v[92:95], v[140:143], v[206:209], 0
	v_mfma_f32_16x16x32_bf16 v[88:91], v[166:169], v[206:209], 0
	v_mfma_f32_16x16x32_bf16 v[76:79], v[140:143], v[214:217], 0
	v_mfma_f32_16x16x32_bf16 v[72:75], v[166:169], v[214:217], 0
	v_mfma_f32_16x16x32_bf16 v[126:129], v[162:165], v[194:197], v[126:129]
	v_mfma_f32_16x16x32_bf16 v[122:125], v[170:173], v[194:197], v[122:125]
	v_mfma_f32_16x16x32_bf16 v[110:113], v[162:165], v[202:205], v[110:113]
	v_mfma_f32_16x16x32_bf16 v[106:109], v[170:173], v[202:205], v[106:109]
	v_mfma_f32_16x16x32_bf16 v[92:95], v[162:165], v[210:213], v[92:95]
	v_mfma_f32_16x16x32_bf16 v[88:91], v[170:173], v[210:213], v[88:91]
	v_mfma_f32_16x16x32_bf16 v[76:79], v[162:165], v[218:221], v[76:79]
	v_mfma_f32_16x16x32_bf16 v[72:75], v[170:173], v[218:221], v[72:75]
	v_mfma_f32_16x16x32_bf16 v[118:121], v[174:177], v[190:193], 0
	v_mfma_f32_16x16x32_bf16 v[114:117], v[182:185], v[190:193], 0
	v_mfma_f32_16x16x32_bf16 v[102:105], v[174:177], v[198:201], 0
	v_mfma_f32_16x16x32_bf16 v[98:101], v[182:185], v[198:201], 0
	v_mfma_f32_16x16x32_bf16 v[84:87], v[174:177], v[206:209], 0
	v_mfma_f32_16x16x32_bf16 v[80:83], v[182:185], v[206:209], 0
	v_mfma_f32_16x16x32_bf16 v[68:71], v[174:177], v[214:217], 0
	v_mfma_f32_16x16x32_bf16 v[64:67], v[182:185], v[214:217], 0
	v_mfma_f32_16x16x32_bf16 v[118:121], v[178:181], v[194:197], v[118:121]
	v_mfma_f32_16x16x32_bf16 v[114:117], v[186:189], v[194:197], v[114:117]
	v_mfma_f32_16x16x32_bf16 v[102:105], v[178:181], v[202:205], v[102:105]
	v_mfma_f32_16x16x32_bf16 v[98:101], v[186:189], v[202:205], v[98:101]
	v_mfma_f32_16x16x32_bf16 v[84:87], v[178:181], v[210:213], v[84:87]
	v_mfma_f32_16x16x32_bf16 v[80:83], v[186:189], v[210:213], v[80:83]
	v_mfma_f32_16x16x32_bf16 v[68:71], v[178:181], v[218:221], v[68:71]
	v_mfma_f32_16x16x32_bf16 v[64:67], v[186:189], v[218:221], v[64:67]
	s_setprio 0
	s_barrier
	s_add_i32 s54, s54, s8
	v_lshl_add_u64 v[144:145], s[52:53], 0, v[96:97]
	s_mov_b32 m0, s54
	ds_read_b128 v[190:193], v149 offset:16384
	ds_read_b128 v[194:197], v149 offset:17408
	ds_read_b128 v[198:201], v149 offset:18432
	ds_read_b128 v[202:205], v149 offset:19456
	ds_read_b128 v[206:209], v149 offset:20480
	ds_read_b128 v[210:213], v149 offset:21504
	ds_read_b128 v[214:217], v149 offset:22528
	ds_read_b128 v[218:221], v149 offset:23552
	global_load_lds_dwordx4 v[144:145], off
	s_add_i32 m0, s54, 0x2000
	v_lshl_add_u64 v[150:151], s[52:53], 0, v[134:135]
	s_add_u32 s52, s52, s34
	s_addc_u32 s53, s53, s35
	s_add_i32 s50, s50, s8
	global_load_lds_dwordx4 v[150:151], off
	v_lshl_add_u64 v[222:223], s[52:53], 0, v[96:97]
	s_mov_b32 m0, s50
	v_lshl_add_u64 v[224:225], s[52:53], 0, v[134:135]
	global_load_lds_dwordx4 v[222:223], off
	s_add_i32 m0, s50, 0x2000
	v_lshl_add_u64 v[226:227], s[78:79], 0, v[130:131]
	global_load_lds_dwordx4 v[224:225], off
	s_mov_b32 m0, s9
	v_lshl_add_u64 v[228:229], s[78:79], 0, v[132:133]
	global_load_lds_dwordx4 v[226:227], off
	s_mov_b32 m0, s98
	s_nop 0
	global_load_lds_dwordx4 v[228:229], off
	s_waitcnt vmcnt(16)
	s_waitcnt lgkmcnt(0)
	s_barrier
	s_setprio 1
	s_waitcnt lgkmcnt(0)
	v_mfma_f32_16x16x32_bf16 v[60:63], v[140:143], v[190:193], 0
	v_mfma_f32_16x16x32_bf16 v[56:59], v[166:169], v[190:193], 0
	v_mfma_f32_16x16x32_bf16 v[44:47], v[140:143], v[198:201], 0
	v_mfma_f32_16x16x32_bf16 v[40:43], v[166:169], v[198:201], 0
	v_mfma_f32_16x16x32_bf16 v[28:31], v[140:143], v[206:209], 0
	v_mfma_f32_16x16x32_bf16 v[24:27], v[166:169], v[206:209], 0
	v_mfma_f32_16x16x32_bf16 v[12:15], v[140:143], v[214:217], 0
	v_mfma_f32_16x16x32_bf16 v[8:11], v[166:169], v[214:217], 0
	v_mfma_f32_16x16x32_bf16 v[60:63], v[162:165], v[194:197], v[60:63]
	v_mfma_f32_16x16x32_bf16 v[56:59], v[170:173], v[194:197], v[56:59]
	v_mfma_f32_16x16x32_bf16 v[44:47], v[162:165], v[202:205], v[44:47]
	v_mfma_f32_16x16x32_bf16 v[40:43], v[170:173], v[202:205], v[40:43]
	v_mfma_f32_16x16x32_bf16 v[28:31], v[162:165], v[210:213], v[28:31]
	v_mfma_f32_16x16x32_bf16 v[24:27], v[170:173], v[210:213], v[24:27]
	v_mfma_f32_16x16x32_bf16 v[12:15], v[162:165], v[218:221], v[12:15]
	v_mfma_f32_16x16x32_bf16 v[8:11], v[170:173], v[218:221], v[8:11]
	v_mfma_f32_16x16x32_bf16 v[52:55], v[174:177], v[190:193], 0
	v_mfma_f32_16x16x32_bf16 v[48:51], v[182:185], v[190:193], 0
	v_mfma_f32_16x16x32_bf16 v[36:39], v[174:177], v[198:201], 0
	v_mfma_f32_16x16x32_bf16 v[32:35], v[182:185], v[198:201], 0
	v_mfma_f32_16x16x32_bf16 v[20:23], v[174:177], v[206:209], 0
	v_mfma_f32_16x16x32_bf16 v[16:19], v[182:185], v[206:209], 0
	v_mfma_f32_16x16x32_bf16 v[4:7], v[174:177], v[214:217], 0
	v_mfma_f32_16x16x32_bf16 v[0:3], v[182:185], v[214:217], 0
	v_mfma_f32_16x16x32_bf16 v[52:55], v[178:181], v[194:197], v[52:55]
	v_mfma_f32_16x16x32_bf16 v[48:51], v[186:189], v[194:197], v[48:51]
	v_mfma_f32_16x16x32_bf16 v[36:39], v[178:181], v[202:205], v[36:39]
	v_mfma_f32_16x16x32_bf16 v[32:35], v[186:189], v[202:205], v[32:35]
	v_mfma_f32_16x16x32_bf16 v[20:23], v[178:181], v[210:213], v[20:23]
	v_mfma_f32_16x16x32_bf16 v[16:19], v[186:189], v[210:213], v[16:19]
	v_mfma_f32_16x16x32_bf16 v[4:7], v[178:181], v[218:221], v[4:7]
	v_mfma_f32_16x16x32_bf16 v[0:3], v[186:189], v[218:221], v[0:3]
	s_setprio 0
	s_barrier
	s_add_i32 s50, 0, 0x18000
	v_add_u32_e32 v161, s50, v147
	s_add_i32 s54, 0, 0x1c000
	ds_read_b128 v[140:143], v161
	ds_read_b128 v[162:165], v161 offset:1024
	ds_read_b128 v[166:169], v161 offset:2048
	ds_read_b128 v[170:173], v161 offset:3072
	v_add_u32_e32 v161, s54, v147
	ds_read_b128 v[174:177], v161
	ds_read_b128 v[178:181], v161 offset:1024
	ds_read_b128 v[182:185], v161 offset:2048
	ds_read_b128 v[186:189], v161 offset:3072
	s_add_u32 s52, s78, s34
	s_addc_u32 s53, s79, s35
	s_mov_b32 m0, s99
	v_lshl_add_u64 v[230:231], s[52:53], 0, v[130:131]
	ds_read_b128 v[190:193], v149 offset:32768
	ds_read_b128 v[194:197], v149 offset:33792
	ds_read_b128 v[198:201], v149 offset:34816
	ds_read_b128 v[202:205], v149 offset:35840
	ds_read_b128 v[206:209], v149 offset:36864
	ds_read_b128 v[210:213], v149 offset:37888
	ds_read_b128 v[214:217], v149 offset:38912
	ds_read_b128 v[218:221], v149 offset:39936
	global_load_lds_dwordx4 v[230:231], off
	v_lshl_add_u64 v[230:231], s[52:53], 0, v[132:133]
	s_mov_b32 m0, s76
	s_nop 0
	global_load_lds_dwordx4 v[230:231], off
	s_waitcnt vmcnt(16)
	s_waitcnt lgkmcnt(0)
	s_barrier
	s_setprio 1
	s_waitcnt lgkmcnt(0)
	v_mfma_f32_16x16x32_bf16 v[126:129], v[140:143], v[190:193], v[126:129]
	v_mfma_f32_16x16x32_bf16 v[122:125], v[166:169], v[190:193], v[122:125]
	v_mfma_f32_16x16x32_bf16 v[110:113], v[140:143], v[198:201], v[110:113]
	v_mfma_f32_16x16x32_bf16 v[106:109], v[166:169], v[198:201], v[106:109]
	v_mfma_f32_16x16x32_bf16 v[92:95], v[140:143], v[206:209], v[92:95]
	v_mfma_f32_16x16x32_bf16 v[88:91], v[166:169], v[206:209], v[88:91]
	v_mfma_f32_16x16x32_bf16 v[76:79], v[140:143], v[214:217], v[76:79]
	v_mfma_f32_16x16x32_bf16 v[72:75], v[166:169], v[214:217], v[72:75]
	v_mfma_f32_16x16x32_bf16 v[126:129], v[162:165], v[194:197], v[126:129]
	v_mfma_f32_16x16x32_bf16 v[122:125], v[170:173], v[194:197], v[122:125]
	v_mfma_f32_16x16x32_bf16 v[110:113], v[162:165], v[202:205], v[110:113]
	v_mfma_f32_16x16x32_bf16 v[106:109], v[170:173], v[202:205], v[106:109]
	v_mfma_f32_16x16x32_bf16 v[92:95], v[162:165], v[210:213], v[92:95]
	v_mfma_f32_16x16x32_bf16 v[88:91], v[170:173], v[210:213], v[88:91]
	v_mfma_f32_16x16x32_bf16 v[76:79], v[162:165], v[218:221], v[76:79]
	v_mfma_f32_16x16x32_bf16 v[72:75], v[170:173], v[218:221], v[72:75]
	v_mfma_f32_16x16x32_bf16 v[118:121], v[174:177], v[190:193], v[118:121]
	v_mfma_f32_16x16x32_bf16 v[114:117], v[182:185], v[190:193], v[114:117]
	v_mfma_f32_16x16x32_bf16 v[102:105], v[174:177], v[198:201], v[102:105]
	v_mfma_f32_16x16x32_bf16 v[98:101], v[182:185], v[198:201], v[98:101]
	v_mfma_f32_16x16x32_bf16 v[84:87], v[174:177], v[206:209], v[84:87]
	v_mfma_f32_16x16x32_bf16 v[80:83], v[182:185], v[206:209], v[80:83]
	v_mfma_f32_16x16x32_bf16 v[68:71], v[174:177], v[214:217], v[68:71]
	v_mfma_f32_16x16x32_bf16 v[64:67], v[182:185], v[214:217], v[64:67]
	v_mfma_f32_16x16x32_bf16 v[118:121], v[178:181], v[194:197], v[118:121]
	v_mfma_f32_16x16x32_bf16 v[114:117], v[186:189], v[194:197], v[114:117]
	v_mfma_f32_16x16x32_bf16 v[102:105], v[178:181], v[202:205], v[102:105]
	v_mfma_f32_16x16x32_bf16 v[98:101], v[186:189], v[202:205], v[98:101]
	v_mfma_f32_16x16x32_bf16 v[84:87], v[178:181], v[210:213], v[84:87]
	v_mfma_f32_16x16x32_bf16 v[80:83], v[186:189], v[210:213], v[80:83]
	v_mfma_f32_16x16x32_bf16 v[68:71], v[178:181], v[218:221], v[68:71]
	v_mfma_f32_16x16x32_bf16 v[64:67], v[186:189], v[218:221], v[64:67]
	s_setprio 0
	s_barrier
	s_add_i32 s50, s50, s8
	v_lshl_add_u64 v[144:145], v[144:145], 0, s[12:13]
	s_mov_b32 m0, s50
	ds_read_b128 v[190:193], v149 offset:49152
	ds_read_b128 v[194:197], v149 offset:50176
	ds_read_b128 v[198:201], v149 offset:51200
	ds_read_b128 v[202:205], v149 offset:52224
	ds_read_b128 v[206:209], v149 offset:53248
	ds_read_b128 v[210:213], v149 offset:54272
	ds_read_b128 v[214:217], v149 offset:55296
	ds_read_b128 v[218:221], v149 offset:56320
	global_load_lds_dwordx4 v[144:145], off
	v_lshl_add_u64 v[144:145], v[150:151], 0, s[12:13]
	s_add_i32 m0, s50, 0x2000
	s_add_i32 s50, s54, s8
	global_load_lds_dwordx4 v[144:145], off
	v_lshl_add_u64 v[144:145], v[222:223], 0, s[12:13]
	s_mov_b32 m0, s50
	s_nop 0
	global_load_lds_dwordx4 v[144:145], off
	v_lshl_add_u64 v[144:145], v[224:225], 0, s[12:13]
	s_add_i32 m0, s50, 0x2000
	s_nop 0
	global_load_lds_dwordx4 v[144:145], off
	v_lshl_add_u64 v[144:145], v[226:227], 0, s[12:13]
	s_mov_b32 m0, s77
	s_nop 0
	global_load_lds_dwordx4 v[144:145], off
	v_lshl_add_u64 v[144:145], v[228:229], 0, s[12:13]
	s_mov_b32 m0, s86
	s_nop 0
	global_load_lds_dwordx4 v[144:145], off
	s_waitcnt vmcnt(8)
	s_waitcnt lgkmcnt(0)
	s_barrier
	s_setprio 1
	s_waitcnt lgkmcnt(0)
	v_mfma_f32_16x16x32_bf16 v[60:63], v[140:143], v[190:193], v[60:63]
	v_mfma_f32_16x16x32_bf16 v[56:59], v[166:169], v[190:193], v[56:59]
	v_mfma_f32_16x16x32_bf16 v[44:47], v[140:143], v[198:201], v[44:47]
	v_mfma_f32_16x16x32_bf16 v[40:43], v[166:169], v[198:201], v[40:43]
	v_mfma_f32_16x16x32_bf16 v[28:31], v[140:143], v[206:209], v[28:31]
	v_mfma_f32_16x16x32_bf16 v[24:27], v[166:169], v[206:209], v[24:27]
	v_mfma_f32_16x16x32_bf16 v[12:15], v[140:143], v[214:217], v[12:15]
	v_mfma_f32_16x16x32_bf16 v[8:11], v[166:169], v[214:217], v[8:11]
	v_mfma_f32_16x16x32_bf16 v[60:63], v[162:165], v[194:197], v[60:63]
	v_mfma_f32_16x16x32_bf16 v[56:59], v[170:173], v[194:197], v[56:59]
	v_mfma_f32_16x16x32_bf16 v[44:47], v[162:165], v[202:205], v[44:47]
	v_mfma_f32_16x16x32_bf16 v[40:43], v[170:173], v[202:205], v[40:43]
	v_mfma_f32_16x16x32_bf16 v[28:31], v[162:165], v[210:213], v[28:31]
	v_mfma_f32_16x16x32_bf16 v[24:27], v[170:173], v[210:213], v[24:27]
	v_mfma_f32_16x16x32_bf16 v[12:15], v[162:165], v[218:221], v[12:15]
	v_mfma_f32_16x16x32_bf16 v[8:11], v[170:173], v[218:221], v[8:11]
	v_mfma_f32_16x16x32_bf16 v[52:55], v[174:177], v[190:193], v[52:55]
	v_mfma_f32_16x16x32_bf16 v[48:51], v[182:185], v[190:193], v[48:51]
	v_mfma_f32_16x16x32_bf16 v[36:39], v[174:177], v[198:201], v[36:39]
	v_mfma_f32_16x16x32_bf16 v[32:35], v[182:185], v[198:201], v[32:35]
	v_mfma_f32_16x16x32_bf16 v[20:23], v[174:177], v[206:209], v[20:23]
	v_mfma_f32_16x16x32_bf16 v[16:19], v[182:185], v[206:209], v[16:19]
	v_mfma_f32_16x16x32_bf16 v[4:7], v[174:177], v[214:217], v[4:7]
	v_mfma_f32_16x16x32_bf16 v[0:3], v[182:185], v[214:217], v[0:3]
	v_mfma_f32_16x16x32_bf16 v[52:55], v[178:181], v[194:197], v[52:55]
	v_mfma_f32_16x16x32_bf16 v[48:51], v[186:189], v[194:197], v[48:51]
	v_mfma_f32_16x16x32_bf16 v[36:39], v[178:181], v[202:205], v[36:39]
	v_mfma_f32_16x16x32_bf16 v[32:35], v[186:189], v[202:205], v[32:35]
	v_mfma_f32_16x16x32_bf16 v[20:23], v[178:181], v[210:213], v[20:23]
	v_mfma_f32_16x16x32_bf16 v[16:19], v[186:189], v[210:213], v[16:19]
	v_mfma_f32_16x16x32_bf16 v[4:7], v[178:181], v[218:221], v[4:7]
	v_mfma_f32_16x16x32_bf16 v[0:3], v[186:189], v[218:221], v[0:3]
	s_setprio 0
	s_barrier
	s_add_u32 s42, s42, 0x100
	s_addc_u32 s43, s43, 0
	s_add_u32 s48, s48, 0x100
	s_addc_u32 s49, s49, 0
	s_cmp_ge_u32 s51, s64
	s_mov_b32 s50, s51
	s_cbranch_scc0 .LBB0_333
	s_branch .Lk_done
